# B-attention: only the high-priority wave of each SIMD issues the stage LDS-DMAs (its own 8 pieces + its low-priority neighbour's 8), on top of the v133 stack
# baseline (speedup 1.0000x reference)
; #define LAS __attribute__((address_space(3)))
; #define ATT_STAGE(t_, buf_) do { const char* gb_ = gbase + (size_t)(t_) * tstep; _Pragma("unroll") for (int j_ = 0; j_ < NPW * REP_DMA; ++j_) \
;         __builtin_amdgcn_global_load_lds((const unsigned*)(gb_ + ATT_CJ(j_ % NPW) + vbase), (LAS unsigned*)(lds + (buf_) * STAGE + (wid * NPW + j_ % NPW) * 1024), 16, 0, 0); } while (0)
; template <int DV, int NMAP> ...
;     ...
;     const int loff = (fr * 64 + fq * 16) ^ (((fr >> 3) & 1) << 5);
;     f32x4 o[DV / 16][2];
; #pragma unroll
;     for (int db = 0; db < DV / 16; ++db) { o[db][0] = (f32x4){0.f, 0.f, 0.f, 0.f}; o[db][1] = (f32x4){0.f, 0.f, 0.f, 0.f}; }
;     float lsum[2] = {0.f, 0.f};
;     const LAS float* tab = (const LAS float*)(lds + TAB_OFF);
;     asm volatile("s_waitcnt vmcnt(0)" ::: "memory");
;     ATT_STAGE(T0, 0);
;     if ((wid >> 2) ^ (wid & 1)) __builtin_amdgcn_s_setprio(2);
.LBB0_315:
	s_add_u32 s70, s88, s44
	s_addc_u32 s71, s89, s45
	s_lshl_b32 s34, s34, 13
	s_add_i32 s34, s34, 0
	v_lshl_add_u64 v[4:5], s[70:71], 0, v[204:205]
	s_mov_b32 m0, s34
	v_lshl_add_u64 v[6:7], v[4:5], 0, 64
	global_load_lds_dwordx4 v204, s[70:71]
	s_add_i32 m0, s34, 0x400
	v_mov_b64_e32 v[214:215], 0x400
	global_load_lds_dwordx4 v[6:7], off
	v_lshl_add_u64 v[6:7], v[4:5], 0, s[72:73]
	s_add_i32 m0, s34, 0x800
	s_nop 0
	global_load_lds_dwordx4 v[6:7], off
	v_lshl_add_u64 v[6:7], v[4:5], 0, s[68:69]
	s_add_i32 m0, s34, 0xc00
	s_nop 0
	global_load_lds_dwordx4 v[6:7], off
	v_lshl_add_u64 v[6:7], v[4:5], 0, s[38:39]
	s_add_i32 m0, s34, 0x1000
	s_nop 0
	global_load_lds_dwordx4 v[6:7], off
	v_lshl_add_u64 v[6:7], v[4:5], 0, s[16:17]
	s_add_i32 m0, s34, 0x1400
	s_nop 0
	global_load_lds_dwordx4 v[6:7], off
	v_lshl_add_u64 v[6:7], v[4:5], 0, s[10:11]
	s_add_i32 m0, s34, 0x1800
	v_lshl_add_u64 v[4:5], v[4:5], 0, s[8:9]
	global_load_lds_dwordx4 v[6:7], off
	s_add_i32 m0, s34, 0x1c00
	s_bfe_u32 s8, s20, 0x10006
	global_load_lds_dwordx4 v[4:5], off
	s_mov_b32 s32, 0
	s_cmp_eq_u32 s21, s8
	s_cbranch_scc1 .LBB0_317
	s_setprio 2
	s_mov_b32 s32, 1
.LBB0_317:
	s_mov_b32 s26, 0x200000
	s_mov_b32 s27, 0
	s_mov_b32 s28, 0x2000
	s_cmp_lg_u32 s21, 0
	s_cbranch_scc1 .Lhs_v
	s_mov_b32 s26, 0xffffff80
	s_mov_b32 s27, -1
	s_mov_b32 s28, 0xffffe000

; #define ATT_STAGE(t_, buf_) do { const char* gb_ = gbase + (size_t)(t_) * tstep; _Pragma("unroll") for (int j_ = 0; j_ < NPW * REP_DMA; ++j_) \
;         __builtin_amdgcn_global_load_lds((const unsigned*)(gb_ + ATT_CJ(j_ % NPW) + vbase), (LAS unsigned*)(lds + (buf_) * STAGE + (wid * NPW + j_ % NPW) * 1024), 16, 0, 0); } while (0)
; template <int DV, int NMAP> ...
;     ...
;     for (int t = T0; t <= T1; ++t) {
;         const int cur = (t - T0) & 1;
;         asm volatile("s_waitcnt vmcnt(0)" ::: "memory");
;         asm volatile("s_waitcnt lgkmcnt(0)" ::: "memory"); __builtin_amdgcn_s_barrier(); asm volatile("" ::: "memory");
;         const bool inr = (t >= lo_w && t <= cw);
;         if (t < T1 && (isk || !inr)) ATT_STAGE(t + 1, cur ^ 1);
.LBB0_320:
	s_and_b32 s52, s84, 1
	s_cmp_le_u32 s84, s37
	s_cselect_b64 s[44:45], -1, 0
	s_cmp_gt_u32 s84, s37
	s_waitcnt vmcnt(0)
	s_cselect_b64 s[70:71], -1, 0
	s_cmp_le_u32 s84, s35
	s_waitcnt lgkmcnt(0)
	s_barrier
	s_cselect_b64 s[78:79], -1, 0
	s_or_b64 s[70:71], s[4:5], s[70:71]
	s_and_b64 s[70:71], s[78:79], s[70:71]
	s_andn2_b64 vcc, exec, s[70:71]
	s_cbranch_vccnz .LBB0_322
	s_cmp_eq_u32 s32, 0
	s_cbranch_scc1 .LBB0_322
	s_lshl_b32 s53, s52, 16
	s_xor_b32 s53, s53, 0x10000
	s_add_i32 s53, s34, s53
	s_mov_b32 m0, s53
	v_lshl_add_u64 v[160:161], v[220:221], 0, 64
	global_load_lds_dwordx4 v[220:221], off
	s_add_i32 m0, s53, 0x400
	s_nop 0
	global_load_lds_dwordx4 v[160:161], off
	v_lshl_add_u64 v[160:161], v[220:221], 0, s[8:9]
	s_add_i32 m0, s53, 0x800
	s_nop 0
	global_load_lds_dwordx4 v[160:161], off
	v_lshl_add_u64 v[160:161], v[220:221], 0, s[10:11]
	s_add_i32 m0, s53, 0xc00
	s_nop 0
	global_load_lds_dwordx4 v[160:161], off
	v_lshl_add_u64 v[160:161], v[220:221], 0, s[16:17]
	s_add_i32 m0, s53, 0x1000
	s_nop 0
	global_load_lds_dwordx4 v[160:161], off
	v_lshl_add_u64 v[160:161], v[220:221], 0, s[38:39]
	s_add_i32 m0, s53, 0x1400
	s_nop 0
	global_load_lds_dwordx4 v[160:161], off
	v_lshl_add_u64 v[160:161], v[220:221], 0, s[72:73]
	s_add_i32 m0, s53, 0x1800
	s_nop 0
	global_load_lds_dwordx4 v[160:161], off
	v_lshl_add_u64 v[160:161], v[220:221], 0, s[76:77]
	s_add_i32 m0, s53, 0x1c00
	s_nop 0
	global_load_lds_dwordx4 v[160:161], off
	v_lshl_add_u64 v[162:163], v[220:221], 0, s[26:27]
	s_add_i32 s33, s53, s28
	s_mov_b32 m0, s33
	s_nop 0
	global_load_lds_dwordx4 v[162:163], off
	v_lshl_add_u64 v[160:161], v[162:163], 0, 64
	s_add_i32 m0, s33, 0x400
	s_nop 0
	global_load_lds_dwordx4 v[160:161], off
	v_lshl_add_u64 v[160:161], v[162:163], 0, s[8:9]
	s_add_i32 m0, s33, 0x800
	s_nop 0
	global_load_lds_dwordx4 v[160:161], off
	v_lshl_add_u64 v[160:161], v[162:163], 0, s[10:11]
	s_add_i32 m0, s33, 0xc00
	s_nop 0
	global_load_lds_dwordx4 v[160:161], off
	v_lshl_add_u64 v[160:161], v[162:163], 0, s[16:17]
	s_add_i32 m0, s33, 0x1000
	s_nop 0
	global_load_lds_dwordx4 v[160:161], off
	v_lshl_add_u64 v[160:161], v[162:163], 0, s[38:39]
	s_add_i32 m0, s33, 0x1400
	s_nop 0
	global_load_lds_dwordx4 v[160:161], off
	v_lshl_add_u64 v[160:161], v[162:163], 0, s[72:73]
	s_add_i32 m0, s33, 0x1800
	s_nop 0
	global_load_lds_dwordx4 v[160:161], off
	v_lshl_add_u64 v[160:161], v[162:163], 0, s[76:77]
	s_add_i32 m0, s33, 0x1c00
	s_nop 0
	global_load_lds_dwordx4 v[160:161], off

; template <int N> __device__ __forceinline__ void lgkm_pin(bf16x8& f) { (void)f; asm volatile("s_waitcnt lgkmcnt(%0)" :: "n"(N) : "memory"); }
; #define ATT_STAGE(t_, buf_) do { const char* gb_ = gbase + (size_t)(t_) * tstep; _Pragma("unroll") for (int j_ = 0; j_ < NPW * REP_DMA; ++j_) \
;         __builtin_amdgcn_global_load_lds((const unsigned*)(gb_ + ATT_CJ(j_ % NPW) + vbase), (LAS unsigned*)(lds + (buf_) * STAGE + (wid * NPW + j_ % NPW) * 1024), 16, 0, 0); } while (0)
; #define ATT_KLD(i_) lds_rd(stk, (((i_) >> 2) >> 1) * 8192 + (((i_) & 3) * 2 + (((i_) >> 2) & 1)) * 1024)
; template <int DV, int NMAP> ...
;     ...
;             { bf16x8 f0 = ATT_KLD(0), f1 = ATT_KLD(1), f2 = ATT_KLD(2);
; #pragma unroll
;               for (int i = 0; i < 16; ++i) {
;                   bf16x8 cur = f0; f0 = f1; f1 = f2; if (i + 3 < 16) f2 = ATT_KLD(i + 3);
;                   if (i + 3 < 16) lgkm_pin<3>(cur); else if (i + 2 < 16) lgkm_pin<2>(cur); else if (i + 1 < 16) lgkm_pin<1>(cur); else lgkm_pin<0>(cur);
;                   __builtin_amdgcn_sched_barrier(0);
;                   s[i & 3][0] = __builtin_amdgcn_mfma_f32_16x16x32_bf16(cur, q[0][i >> 2], s[i & 3][0], 0, 0, 0);
;                   s[i & 3][1] = __builtin_amdgcn_mfma_f32_16x16x32_bf16(cur, q[1][i >> 2], s[i & 3][1], 0, 0, 0);
;                   __builtin_amdgcn_sched_barrier(0);
;               } }
;             if (t < T1 && !isk) ATT_STAGE(t + 1, cur ^ 1);
.Lbt_qk:
	s_waitcnt lgkmcnt(3)
	s_nop 0
	v_mfma_f32_16x16x32_bf16 v[176:179], v[160:163], v[124:127], 0
	v_mfma_f32_16x16x32_bf16 v[160:163], v[160:163], v[140:143], 0
	ds_read_b128 v[180:183], v204 offset:0x400
	s_waitcnt lgkmcnt(3)
	v_mfma_f32_16x16x32_bf16 v[184:187], v[164:167], v[124:127], 0
	v_mfma_f32_16x16x32_bf16 v[164:167], v[164:167], v[140:143], 0
	ds_read_b128 v[188:191], v204 offset:0xc00
	s_waitcnt lgkmcnt(3)
	v_mfma_f32_16x16x32_bf16 v[192:195], v[168:171], v[124:127], 0
	v_mfma_f32_16x16x32_bf16 v[168:171], v[168:171], v[140:143], 0
	ds_read_b128 v[196:199], v204 offset:0x1400
	s_waitcnt lgkmcnt(3)
	v_mfma_f32_16x16x32_bf16 v[200:203], v[172:175], v[124:127], 0
	v_mfma_f32_16x16x32_bf16 v[172:175], v[172:175], v[140:143], 0
	ds_read_b128 v[240:243], v204 offset:0x1c00
	s_waitcnt lgkmcnt(3)
	v_mfma_f32_16x16x32_bf16 v[176:179], v[180:183], v[128:131], v[176:179]
	v_mfma_f32_16x16x32_bf16 v[160:163], v[180:183], v[144:147], v[160:163]
	ds_read_b128 v[180:183], v204 offset:0x2000
	s_waitcnt lgkmcnt(3)
	v_mfma_f32_16x16x32_bf16 v[164:167], v[188:191], v[144:147], v[164:167]
	v_mfma_f32_16x16x32_bf16 v[184:187], v[188:191], v[128:131], v[184:187]
	ds_read_b128 v[188:191], v204 offset:0x2800
	s_waitcnt lgkmcnt(3)
	v_mfma_f32_16x16x32_bf16 v[168:171], v[196:199], v[144:147], v[168:171]
	v_mfma_f32_16x16x32_bf16 v[192:195], v[196:199], v[128:131], v[192:195]
	ds_read_b128 v[196:199], v204 offset:0x3000
	s_waitcnt lgkmcnt(3)
	v_mfma_f32_16x16x32_bf16 v[172:175], v[240:243], v[144:147], v[172:175]
	v_mfma_f32_16x16x32_bf16 v[200:203], v[240:243], v[128:131], v[200:203]
	ds_read_b128 v[240:243], v204 offset:0x3800
	s_waitcnt lgkmcnt(3)
	v_mfma_f32_16x16x32_bf16 v[176:179], v[180:183], v[132:135], v[176:179]
	v_mfma_f32_16x16x32_bf16 v[160:163], v[180:183], v[148:151], v[160:163]
	ds_read_b128 v[180:183], v204 offset:0x2400
	s_waitcnt lgkmcnt(3)
	v_mfma_f32_16x16x32_bf16 v[164:167], v[188:191], v[148:151], v[164:167]
	v_mfma_f32_16x16x32_bf16 v[184:187], v[188:191], v[132:135], v[184:187]
	ds_read_b128 v[244:247], v204 offset:0x2c00
	s_waitcnt lgkmcnt(3)
	v_mfma_f32_16x16x32_bf16 v[168:171], v[196:199], v[148:151], v[168:171]
	v_mfma_f32_16x16x32_bf16 v[192:195], v[196:199], v[132:135], v[192:195]
	ds_read_b128 v[248:251], v204 offset:0x3400
	s_waitcnt lgkmcnt(3)
	v_mfma_f32_16x16x32_bf16 v[200:203], v[240:243], v[132:135], v[200:203]
	v_mfma_f32_16x16x32_bf16 v[240:243], v[240:243], v[148:151], v[172:175]
	ds_read_b128 v[206:209], v204 offset:0x3c00
	s_waitcnt lgkmcnt(3)
	v_mfma_f32_16x16x32_bf16 v[196:199], v[180:183], v[136:139], v[176:179]
	v_mfma_f32_16x16x32_bf16 v[180:183], v[180:183], v[152:155], v[160:163]
	s_waitcnt lgkmcnt(2)
	v_mfma_f32_16x16x32_bf16 v[188:191], v[244:247], v[136:139], v[184:187]
	v_mfma_f32_16x16x32_bf16 v[176:179], v[244:247], v[152:155], v[164:167]
	s_waitcnt lgkmcnt(1)
	v_mfma_f32_16x16x32_bf16 v[172:175], v[248:251], v[136:139], v[192:195]
	v_mfma_f32_16x16x32_bf16 v[168:171], v[248:251], v[152:155], v[168:171]
	s_waitcnt lgkmcnt(0)
	v_mfma_f32_16x16x32_bf16 v[164:167], v[206:209], v[136:139], v[200:203]
	v_mfma_f32_16x16x32_bf16 v[160:163], v[206:209], v[152:155], v[240:243]
	s_cmp_gt_u32 s84, s35
	s_cselect_b64 s[52:53], -1, 0
	s_or_b64 s[52:53], s[4:5], s[52:53]
	s_and_b64 vcc, exec, s[52:53]
	s_cbranch_vccnz .LBB0_325
	s_cmp_eq_u32 s32, 0
	s_cbranch_scc1 .LBB0_325
	s_xor_b32 s45, s45, 0x10000
	s_add_i32 s45, s34, s45
	s_mov_b32 m0, s45
	v_lshl_add_u64 v[184:185], v[220:221], 0, 64
	global_load_lds_dwordx4 v[220:221], off
	s_add_i32 m0, s45, 0x400
	s_mov_b64 s[52:53], 0x100040
	global_load_lds_dwordx4 v[184:185], off
	v_lshl_add_u64 v[184:185], v[220:221], 0, s[24:25]
	s_add_i32 m0, s45, 0x800
	s_nop 0
	global_load_lds_dwordx4 v[184:185], off
	v_lshl_add_u64 v[184:185], v[220:221], 0, s[12:13]
	s_add_i32 m0, s45, 0xc00
	s_nop 0
	global_load_lds_dwordx4 v[184:185], off
	v_lshl_add_u64 v[184:185], v[220:221], 0, s[30:31]
	s_add_i32 m0, s45, 0x1000
	s_nop 0
	global_load_lds_dwordx4 v[184:185], off
	v_lshl_add_u64 v[184:185], v[220:221], 0, s[52:53]
	s_add_i32 m0, s45, 0x1400
	s_mov_b64 s[52:53], 0x180000
	global_load_lds_dwordx4 v[184:185], off
	v_lshl_add_u64 v[184:185], v[220:221], 0, s[52:53]
	s_add_i32 m0, s45, 0x1800
	s_mov_b64 s[52:53], 0x180040
	global_load_lds_dwordx4 v[184:185], off
	v_lshl_add_u64 v[184:185], v[220:221], 0, s[52:53]
	s_add_i32 m0, s45, 0x1c00
	s_nop 0
	global_load_lds_dwordx4 v[184:185], off
	v_lshl_add_u64 v[186:187], v[220:221], 0, s[26:27]
	s_add_i32 s33, s45, s28
	s_mov_b32 m0, s33
	s_nop 0
	global_load_lds_dwordx4 v[186:187], off
	v_lshl_add_u64 v[184:185], v[186:187], 0, 64
	s_add_i32 m0, s33, 0x400
	s_nop 0
	global_load_lds_dwordx4 v[184:185], off
	v_lshl_add_u64 v[184:185], v[186:187], 0, s[24:25]
	s_add_i32 m0, s33, 0x800
	s_nop 0
	global_load_lds_dwordx4 v[184:185], off
	v_lshl_add_u64 v[184:185], v[186:187], 0, s[12:13]
	s_add_i32 m0, s33, 0xc00
	s_nop 0
	global_load_lds_dwordx4 v[184:185], off
	v_lshl_add_u64 v[184:185], v[186:187], 0, s[30:31]
	s_add_i32 m0, s33, 0x1000
	s_nop 0
	global_load_lds_dwordx4 v[184:185], off
	s_mov_b64 s[52:53], 0x100040
	v_lshl_add_u64 v[184:185], v[186:187], 0, s[52:53]
	s_add_i32 m0, s33, 0x1400
	s_nop 0
	global_load_lds_dwordx4 v[184:185], off
	s_mov_b64 s[52:53], 0x180000
	v_lshl_add_u64 v[184:185], v[186:187], 0, s[52:53]
	s_add_i32 m0, s33, 0x1800
	s_nop 0
	global_load_lds_dwordx4 v[184:185], off
	s_mov_b64 s[52:53], 0x180040
	v_lshl_add_u64 v[184:185], v[186:187], 0, s[52:53]
	s_add_i32 m0, s33, 0x1c00
	s_nop 0
	global_load_lds_dwordx4 v[184:185], off

; __global__ void __launch_bounds__(512, 2) trunk_fwd(Args a) {
;     ...
;                 for (int rep = 0; rep < REP_ATTB; ++rep)
;                 for (int u = u0; u < 128 * 8; u += G) {
;                     const int h = u & 7, j = u >> 3, ii = j & 31, r = j >> 5;
;                     const int qblk = (r == 0) ? 127 - ii : (r == 1) ? 64 + ii : (r == 2) ? 63 - ii : ii;
;     ...
;                     att::attn_unit<256, 2>(lds, QK, VT, OB, 128 * qblk, 2 * h, 256 * h, 0, 2 * qblk + 1, false, tabB + h * 256, lam, 1.0f - li, (const float*)(ws + WS_BSUB) + (size_t)i * 256);
;     ...
;                 }
;             }
;         }
;         SEAM();
.LBB0_331:
	s_mov_b64 s[26:27], 0x80
	s_mov_b64 s[28:29], 0x80080
	s_ashr_i32 s33, s48, 31
	s_mov_b64 s[4:5], 0
	v_mov_b32_e32 v224, 1
